# v59 + P3: CHS load issued first and waited with vmcnt(61) so the gate recurrence starts before the hoisted bulk loads land
# speedup vs baseline: 1.0200x; 1.0023x over previous
.LBB0_948:
	s_cmp_lt_i32 s4, 4
	s_cselect_b64 s[0:1], -1, 0
	s_cmp_gt_i32 s5, 3
	s_cselect_b64 s[2:3], -1, 0
	s_and_b64 s[0:1], s[0:1], s[2:3]
	s_andn2_b64 vcc, exec, s[0:1]
	s_cbranch_vccnz .LBB0_1031
	s_waitcnt vmcnt(0)
	v_mov_b32_e32 v84, v0
	s_ashr_i32 s0, s92, 3
	s_nop 0
	v_cmp_gt_i32_e32 vcc, 32, v84
	v_lshl_add_u32 v201, v84, 2, 0
	v_lshl_add_u32 v210, s0, 5, v84
	s_and_saveexec_b64 s[2:3], vcc
	s_cbranch_execz .Lmy_p3_noload
	v_ashrrev_i32_e32 v211, 31, v210
	v_lshl_add_u64 v[202:203], v[210:211], 2, s[96:97]
	v_add_co_u32_e32 v202, vcc, 0x2bc80000, v202
	s_nop 1
	v_addc_co_u32_e32 v203, vcc, 0, v203, vcc
	global_load_dword v202, v[202:203], off
.Lmy_p3_noload:
	s_or_b64 exec, exec, s[2:3]
	s_and_b32 s14, s92, 7
	s_mov_b32 s10, s0
	s_ashr_i32 s11, s0, 31
	s_lshl_b64 s[12:13], s[10:11], 12
	v_ashrrev_i32_e32 v230, 4, v84
	v_lshlrev_b32_e32 v236, 4, v84
	v_mov_b32_e32 v237, 0
	v_lshl_add_u32 v232, s14, 5, v230
	v_and_b32_e32 v236, 0xf0, v236
	v_ashrrev_i32_e32 v233, 31, v232
	v_lshlrev_b32_e32 v236, 1, v236
	v_lshl_add_u64 v[234:235], s[12:13], 0, v[232:233]
	v_lshlrev_b64 v[234:235], 9, v[234:235]
	v_lshl_add_u64 v[234:235], s[96:97], 0, v[234:235]
	v_lshl_add_u64 v[238:239], v[234:235], 0, v[236:237]
	s_mov_b64 s[12:13], 0x23b80000
	v_lshl_add_u64 v[240:241], v[238:239], 0, s[12:13]
	global_load_dwordx4 v[78:81], v[240:241], off nt
	global_load_dwordx4 v[74:77], v[240:241], off offset:16 nt
	s_mov_b64 s[12:13], 0x23ba0000
	v_lshl_add_u64 v[242:243], v[238:239], 0, s[12:13]
	global_load_dwordx4 v[62:65], v[242:243], off nt
	global_load_dwordx4 v[50:53], v[242:243], off offset:16 nt
	s_mov_b64 s[12:13], 0x23bc0000
	v_lshl_add_u64 v[240:241], v[238:239], 0, s[12:13]
	global_load_dwordx4 v[46:49], v[240:241], off nt
	global_load_dwordx4 v[42:45], v[240:241], off offset:16 nt
	s_mov_b64 s[12:13], 0x23be0000
	v_lshl_add_u64 v[242:243], v[238:239], 0, s[12:13]
	global_load_dwordx4 v[38:41], v[242:243], off nt
	global_load_dwordx4 v[34:37], v[242:243], off offset:16 nt
	s_mov_b64 s[12:13], 0x23c00000
	v_lshl_add_u64 v[240:241], v[238:239], 0, s[12:13]
	global_load_dwordx4 v[30:33], v[240:241], off nt
	global_load_dwordx4 v[26:29], v[240:241], off offset:16 nt
	s_mov_b64 s[12:13], 0x23c20000
	v_lshl_add_u64 v[242:243], v[238:239], 0, s[12:13]
	global_load_dwordx4 v[22:25], v[242:243], off nt
	global_load_dwordx4 v[18:21], v[242:243], off offset:16 nt
	s_mov_b64 s[12:13], 0x23c40000
	v_lshl_add_u64 v[240:241], v[238:239], 0, s[12:13]
	global_load_dwordx4 v[14:17], v[240:241], off nt
	global_load_dwordx4 v[10:13], v[240:241], off offset:16 nt
	s_mov_b64 s[12:13], 0x23c60000
	v_lshl_add_u64 v[242:243], v[238:239], 0, s[12:13]
	global_load_dwordx4 v[6:9], v[242:243], off nt
	global_load_dwordx4 v[2:5], v[242:243], off offset:16 nt
	s_mov_b64 s[12:13], 0x23c80000
	v_lshl_add_u64 v[240:241], v[238:239], 0, s[12:13]
	global_load_dwordx4 v[110:113], v[240:241], off nt
	global_load_dwordx4 v[114:117], v[240:241], off offset:16 nt
	s_mov_b64 s[12:13], 0x23ca0000
	v_lshl_add_u64 v[242:243], v[238:239], 0, s[12:13]
	global_load_dwordx4 v[118:121], v[242:243], off nt
	global_load_dwordx4 v[122:125], v[242:243], off offset:16 nt
	s_mov_b64 s[12:13], 0x23cc0000
	v_lshl_add_u64 v[240:241], v[238:239], 0, s[12:13]
	global_load_dwordx4 v[126:129], v[240:241], off nt
	global_load_dwordx4 v[130:133], v[240:241], off offset:16 nt
	s_mov_b64 s[12:13], 0x23ce0000
	v_lshl_add_u64 v[242:243], v[238:239], 0, s[12:13]
	global_load_dwordx4 v[134:137], v[242:243], off nt
	global_load_dwordx4 v[138:141], v[242:243], off offset:16 nt
	s_mov_b64 s[12:13], 0x23d00000
	v_lshl_add_u64 v[240:241], v[238:239], 0, s[12:13]
	global_load_dwordx4 v[142:145], v[240:241], off nt
	global_load_dwordx4 v[146:149], v[240:241], off offset:16 nt
	s_mov_b64 s[12:13], 0x23d20000
	v_lshl_add_u64 v[242:243], v[238:239], 0, s[12:13]
	global_load_dwordx4 v[150:153], v[242:243], off nt
	global_load_dwordx4 v[154:157], v[242:243], off offset:16 nt
	s_mov_b64 s[12:13], 0x23d40000
	v_lshl_add_u64 v[240:241], v[238:239], 0, s[12:13]
	global_load_dwordx4 v[158:161], v[240:241], off nt
	global_load_dwordx4 v[162:165], v[240:241], off offset:16 nt
	s_mov_b64 s[12:13], 0x23d60000
	v_lshl_add_u64 v[242:243], v[238:239], 0, s[12:13]
	global_load_dwordx4 v[166:169], v[242:243], off nt
	global_load_dwordx4 v[170:173], v[242:243], off offset:16 nt
	v_readlane_b32 s10, v245, 21
	v_readlane_b32 s11, v245, 22
	v_readlane_b32 s12, v245, 23
	v_readlane_b32 s13, v245, 24
	v_and_b32_e32 v230, 63, v84
	v_lshlrev_b32_e32 v231, 2, v230
	v_lshlrev_b32_e32 v232, 3, v230
	s_nop 4
	global_load_dword v106, v231, s[10:11]
	global_load_dword v107, v231, s[12:13]
	v_readlane_b32 s10, v245, 25
	v_readlane_b32 s11, v245, 26
	v_readlane_b32 s12, v245, 27
	v_readlane_b32 s13, v245, 28
	v_readlane_b32 s14, v245, 29
	v_readlane_b32 s15, v245, 30
	s_nop 4
	global_load_dword v108, v231, s[10:11]
	global_load_dword v109, v231, s[12:13]
	global_load_dwordx2 v[174:175], v232, s[14:15]
	v_readfirstlane_b32 s10, v84
	s_ashr_i32 s10, s10, 6
	s_lshl_b32 s11, s92, 3
	s_add_i32 s10, s10, s11
	s_lshl_b32 s10, s10, 1
	s_ashr_i32 s11, s10, 31
	s_lshl_b64 s[12:13], s[10:11], 11
	s_add_u32 s12, s12, 0x19000000
	s_addc_u32 s13, s13, 0
	s_add_u32 s12, s12, s96
	s_addc_u32 s13, s13, s97
	global_load_dword v176, v231, s[12:13]
	global_load_dword v177, v231, s[12:13] offset:256
	global_load_dword v178, v231, s[12:13] offset:512
	global_load_dword v179, v231, s[12:13] offset:768
	global_load_dword v180, v231, s[12:13] offset:1024
	global_load_dword v181, v231, s[12:13] offset:1280
	global_load_dword v182, v231, s[12:13] offset:1536
	global_load_dword v183, v231, s[12:13] offset:1792
	s_lshl_b64 s[14:15], s[10:11], 12
	s_add_u32 s14, s14, 0x10f00000
	s_addc_u32 s15, s15, 0
	s_add_u32 s14, s14, s96
	s_addc_u32 s15, s15, s97
	global_load_dword v184, v231, s[14:15] offset:2048
	global_load_dword v185, v231, s[14:15] offset:2304
	global_load_dword v186, v231, s[14:15] offset:2560
	global_load_dword v187, v231, s[14:15] offset:2816
	s_add_u32 s12, s12, 0x800
	s_addc_u32 s13, s13, 0
	global_load_dword v188, v231, s[12:13]
	global_load_dword v189, v231, s[12:13] offset:256
	global_load_dword v190, v231, s[12:13] offset:512
	global_load_dword v191, v231, s[12:13] offset:768
	global_load_dword v192, v231, s[12:13] offset:1024
	global_load_dword v193, v231, s[12:13] offset:1280
	global_load_dword v194, v231, s[12:13] offset:1536
	global_load_dword v195, v231, s[12:13] offset:1792
	s_add_u32 s14, s14, 0x1000
	s_addc_u32 s15, s15, 0
	global_load_dword v196, v231, s[14:15] offset:2048
	global_load_dword v197, v231, s[14:15] offset:2304
	global_load_dword v198, v231, s[14:15] offset:2560
	global_load_dword v199, v231, s[14:15] offset:2816
	v_cmp_gt_i32_e32 vcc, 32, v84
	s_and_saveexec_b64 s[2:3], vcc
	s_cbranch_execz .LBB0_951
	s_waitcnt vmcnt(61)
	ds_write_b32 v201, v202 offset:256
